# v32 + the grid barrier in front of a3+c3 replaced by a scan-done counter (scan workgroups publish their scans with an L2 write-back + counter; every workgroup waits for 136 per layer and acquires); ou
# speedup vs baseline: 1.0043x; 1.0004x over previous
; __device__ __forceinline__ void xcd_barrier(const XcdBarrier& b) {
;     asm volatile("s_waitcnt vmcnt(0)" ::: "memory");
;     __syncthreads();
;     if (threadIdx.x == 0) {
;         unsigned* bar = b.bar;
;         __builtin_amdgcn_s_waitcnt(0);
;         unsigned nloc = b.st[0], nx = b.st[1];
;         if (nloc == 0u) { xcd_barrier_complete(bar, b.x, nloc, nx); b.st[0] = nloc; b.st[1] = nx; }
; __global__ __launch_bounds__(512, 2) void hybrid_fwd(Params P0) {
;     ...
;         if (ph > P0.ph_lo) { if (P0.ph_lo < 0) grid.sync();   xcd_barrier(xb); }
.LBB0_22:
	s_cmp_eq_u32 s94, 4
	s_cbranch_scc1 .Lsd_sync
	s_cmp_eq_u32 s94, 10
	s_cbranch_scc1 .Lsd_sync
	s_waitcnt vmcnt(0)
	s_barrier
	s_mov_b64 s[0:1], exec
	v_readlane_b32 s4, v249, 0
	v_readlane_b32 s5, v249, 1
	s_and_b64 s[4:5], s[0:1], s[4:5]
	s_mov_b64 exec, s[4:5]
	s_cbranch_execz .LBB0_74
	s_waitcnt vmcnt(0)
	v_mov_b32_e32 v0, s73
	s_waitcnt vmcnt(0) expcnt(0) lgkmcnt(0)
	ds_read_b32 v2, v0
	v_mov_b32_e32 v0, s76
	ds_read_b32 v0, v0
	s_waitcnt lgkmcnt(1)
	v_cmp_ne_u32_e32 vcc, 0, v2
	s_cbranch_vccnz .LBB0_38
	s_mov_b32 s10, 1
	s_branch .LBB0_26

; __device__ __forceinline__ unsigned xb_ld(unsigned* p)              { return __hip_atomic_load(p, __ATOMIC_RELAXED, __HIP_MEMORY_SCOPE_AGENT); }
; __device__ __forceinline__ unsigned xb_add(unsigned* p, unsigned v) { return __hip_atomic_fetch_add(p, v, __ATOMIC_RELAXED, __HIP_MEMORY_SCOPE_AGENT); }
; #define XB_SPIN(cond, bar) do { unsigned _sp = 0; while (cond) { __builtin_amdgcn_s_sleep(1); \
;     if ((++_sp & 255u) == 0u) { if (xb_ld(&(bar)[XB_TMO])) break; if (_sp > XB_SPIN_CAP) { atomicAdd(&(bar)[XB_TMO], 1u); break; } } } } while (0)
; __device__ __forceinline__ void xcd_barrier(const XcdBarrier& b) {
;     asm volatile("s_waitcnt vmcnt(0)" ::: "memory");
;     __syncthreads();
;     if (threadIdx.x == 0) {
;         unsigned* bar = b.bar;
;         __builtin_amdgcn_s_waitcnt(0);
;         unsigned nloc = b.st[0], nx = b.st[1];
;         if (nloc == 0u) { xcd_barrier_complete(bar, b.x, nloc, nx); b.st[0] = nloc; b.st[1] = nx; }
;         const unsigned old = xb_add(&bar[XB_XSUB(b.x)], 1u);
;         const unsigned gen = old / nloc;
;         if (old + 1u == (gen + 1u) * nloc) {
;             __builtin_amdgcn_fence(__ATOMIC_RELEASE, "agent");
;             asm volatile("s_waitcnt vmcnt(0)" ::: "memory");
;             const unsigned og = xb_add(&bar[XB_TOP], 1u);
;             const unsigned tg = og / nx;
;             if (og + 1u == (tg + 1u) * nx) xb_add(&bar[XB_TOPGEN], 1u);
;             else XB_SPIN(xb_ld(&bar[XB_TOPGEN]) == tg, bar);
;             __builtin_amdgcn_fence(__ATOMIC_ACQUIRE, "agent");
;             xb_add(&bar[XB_XGEN(b.x)], 1u);
;             asm volatile("s_waitcnt vmcnt(0)" ::: "memory");
;         } else {
;             XB_SPIN(xb_ld(&bar[XB_XGEN(b.x)]) == gen, bar);
;             __builtin_amdgcn_fence(__ATOMIC_ACQUIRE, "agent");
;             asm volatile("s_waitcnt vmcnt(0)" ::: "memory");
;         }
;     }
;     __syncthreads();
; }
.LBB0_74:
	s_or_b64 exec, exec, s[0:1]
	s_waitcnt lgkmcnt(0)
	s_barrier
	s_branch .LBB0_75
.Lsd_sync:
	s_waitcnt vmcnt(0)
	s_barrier
	s_mov_b64 s[0:1], exec
	v_readlane_b32 s4, v249, 0
	v_readlane_b32 s5, v249, 1
	s_and_b64 s[4:5], s[0:1], s[4:5]
	s_mov_b64 exec, s[4:5]
	s_cbranch_execz .Lsd_done
	s_add_u32 s8, s22, 0x33983c00
	s_addc_u32 s9, s23, 0
	s_mov_b32 s6, 0x110
	s_cmp_eq_u32 s94, 4
	s_cselect_b32 s6, 0x88, s6
	v_mov_b32_e32 v1, s6
.Lsd_spin:
	global_load_dword v0, v137, s[8:9] sc1
	s_waitcnt vmcnt(0)
	v_cmp_ge_u32_e32 vcc, v0, v1
	s_nop 4
	s_cbranch_vccnz .Lsd_ok
	s_sleep 1
	s_branch .Lsd_spin
.Lsd_ok:
	buffer_inv sc1
	s_waitcnt vmcnt(0)

; #define LAS __attribute__((address_space(3)))
; __device__ __forceinline__ void b_item(const Params& P, int layer, LAS unsigned char* lds, int item, int tid) {
; __device__ __forceinline__ void phase_scan(const Params& P, int tid) {
;     const int gt = blockIdx.x * 512 + tid, NT = gridDim.x * 512;
;     for (int idx = gt; idx < 49152 + 20480; idx += NT) {
;         if (idx < 49152) {
;             const int bh = idx >> 12, e = (idx & 4095) * 4, b = bh / 6, h = bh % 6, k = e & 127;
;             bf16_t* sp = (bf16_t*)(P.ws + WS_STA) + (size_t)(b * 256 * 6 + h) * 16384 + e;
;             const float* dp = (const float*)(P.ws + WS_DEC) + (size_t)(b * 256 * 6 + h) * 128 + k;
;             f32x4 S = (f32x4){0.f, 0.f, 0.f, 0.f};
;             for (int n0 = 0; n0 < 256; n0 += 16) {
;                 u32x2 d[16]; f32x4 dc[16];
; #pragma unroll
;                 for (int j = 0; j < 16; ++j) { d[j] = *(const u32x2*)(sp + (size_t)(n0 + j) * (6 * 16384)); dc[j] = *(const f32x4*)(dp + (size_t)(n0 + j) * 768); }
; #pragma unroll
;                 for (int j = 0; j < 16; ++j) { u32x2 o; o.x = cvt_pk_bf16(S[0], S[1]); o.y = cvt_pk_bf16(S[2], S[3]);
;                     S[0] = dc[j][0] * S[0] + bflo(d[j].x); S[1] = dc[j][1] * S[1] + bfhi(d[j].x); S[2] = dc[j][2] * S[2] + bflo(d[j].y); S[3] = dc[j][3] * S[3] + bfhi(d[j].y);
;                     *(u32x2*)(sp + (size_t)(n0 + j) * (6 * 16384)) = o; }
;             }
;         } else {
;             const int i2 = idx - 49152, bh = i2 >> 11, e = (i2 & 2047) * 4, b = bh / 5, h = bh % 5;
;             bf16_t* sp = (bf16_t*)(P.ws + WS_STC) + (size_t)(b * 256 * 5 + h) * 8192 + e;
;             const float cd = exp2f(64.f * c_gl2(h));
;             f32x4 S = (f32x4){0.f, 0.f, 0.f, 0.f};
;             for (int n0 = 0; n0 < 256; n0 += 16) {
;                 u32x2 d[16];
; #pragma unroll
;                 for (int j = 0; j < 16; ++j) d[j] = *(const u32x2*)(sp + (size_t)(n0 + j) * (5 * 8192));
; #pragma unroll
;                 for (int j = 0; j < 16; ++j) { u32x2 o; o.x = cvt_pk_bf16(S[0], S[1]); o.y = cvt_pk_bf16(S[2], S[3]);
;                     S[0] = cd * S[0] + bflo(d[j].x); S[1] = cd * S[1] + bfhi(d[j].x); S[2] = cd * S[2] + bflo(d[j].y); S[3] = cd * S[3] + bfhi(d[j].y);
;                     *(u32x2*)(sp + (size_t)(n0 + j) * (5 * 8192)) = o; }
;             }
;         }
;     }
; }
.Lscan_done:
	s_waitcnt vmcnt(0)
	s_barrier
	v_cmp_eq_u32_e32 vcc, 0, v150
	s_and_saveexec_b64 s[0:1], vcc
	s_cbranch_execz .Lsd_sig_skip
	buffer_wbl2 sc1
	s_waitcnt vmcnt(0)
	s_add_u32 s14, s22, 0x33983c00
	s_addc_u32 s15, s23, 0
	v_mov_b32_e32 v0, 1
	global_atomic_add v137, v0, s[14:15]
.Lsd_sig_skip:
	s_or_b64 exec, exec, s[0:1]
.LBB0_139:
	s_or_b64 exec, exec, s[12:13]
	s_waitcnt vmcnt(0)
	v_ashrrev_i32_e32 v0, 31, v150
	v_lshrrev_b32_e32 v0, 28, v0
	v_add_u32_e32 v1, v150, v0
	v_ashrrev_i32_e32 v0, 4, v1
	v_and_b32_e32 v1, -16, v1
	v_sub_u32_e32 v2, v150, v1
	v_ashrrev_i32_e32 v1, 31, v0
	v_lshlrev_b64 v[96:97], 8, v[0:1]
	v_lshlrev_b32_e32 v1, 2, v0
	v_lshlrev_b32_e32 v9, 8, v0
	v_and_b32_e32 v1, 12, v1
	v_bfe_u32 v0, v0, 2, 2
	v_bitop3_b32 v0, v1, v2, v0 bitop3:0x36
	v_add_u32_e32 v151, 0x200, v150
	v_lshl_add_u32 v10, v0, 4, 0
	v_ashrrev_i32_e32 v0, 31, v151
	v_lshrrev_b32_e32 v0, 28, v0
	v_add_u32_e32 v1, v151, v0
	v_ashrrev_i32_e32 v0, 4, v1
	v_and_b32_e32 v1, -16, v1
	v_lshlrev_b32_e32 v98, 3, v2
	v_sub_u32_e32 v2, v151, v1
	v_ashrrev_i32_e32 v1, 31, v0
	v_lshlrev_b64 v[100:101], 8, v[0:1]
	v_lshlrev_b32_e32 v1, 2, v0
	v_lshlrev_b32_e32 v11, 8, v0
	v_and_b32_e32 v1, 12, v1
	v_bfe_u32 v0, v0, 2, 2
	v_bitop3_b32 v0, v1, v2, v0 bitop3:0x36
	v_add_u32_e32 v1, 0x400, v150
	v_lshl_add_u32 v12, v0, 4, 0
	v_ashrrev_i32_e32 v0, 31, v1
	v_lshrrev_b32_e32 v0, 28, v0
	v_lshlrev_b32_e32 v102, 3, v2
	v_add_u32_e32 v2, v1, v0
	v_ashrrev_i32_e32 v0, 4, v2
	v_and_b32_e32 v2, -16, v2
	v_sub_u32_e32 v2, v1, v2
	v_ashrrev_i32_e32 v1, 31, v0
	v_lshlrev_b64 v[104:105], 8, v[0:1]
	v_lshlrev_b32_e32 v1, 2, v0
	v_lshlrev_b32_e32 v13, 8, v0
	v_and_b32_e32 v1, 12, v1
	v_bfe_u32 v0, v0, 2, 2
	v_bitop3_b32 v0, v1, v2, v0 bitop3:0x36
	v_add_u32_e32 v1, 0x600, v150
	v_lshl_add_u32 v14, v0, 4, 0
	v_ashrrev_i32_e32 v0, 31, v1
	v_lshrrev_b32_e32 v0, 28, v0
	v_lshlrev_b32_e32 v106, 3, v2
	v_add_u32_e32 v2, v1, v0
	v_ashrrev_i32_e32 v0, 4, v2
	v_and_b32_e32 v2, -16, v2
	v_sub_u32_e32 v2, v1, v2
	v_ashrrev_i32_e32 v1, 31, v0
	v_lshlrev_b64 v[108:109], 8, v[0:1]
	v_lshlrev_b32_e32 v1, 2, v0
	v_lshlrev_b32_e32 v15, 8, v0
	v_and_b32_e32 v1, 12, v1
	v_bfe_u32 v0, v0, 2, 2
	v_bitop3_b32 v0, v1, v2, v0 bitop3:0x36
	v_add_u32_e32 v1, 0x800, v150
	v_lshl_add_u32 v16, v0, 4, 0
	v_ashrrev_i32_e32 v0, 31, v1
	v_lshrrev_b32_e32 v0, 28, v0
	v_lshlrev_b32_e32 v110, 3, v2
	v_add_u32_e32 v2, v1, v0
	v_ashrrev_i32_e32 v0, 4, v2
	v_and_b32_e32 v2, -16, v2
	v_sub_u32_e32 v2, v1, v2
	v_ashrrev_i32_e32 v1, 31, v0
	v_lshlrev_b64 v[112:113], 8, v[0:1]
	v_lshlrev_b32_e32 v1, 2, v0
	v_lshlrev_b32_e32 v17, 8, v0
	v_and_b32_e32 v1, 12, v1
	v_bfe_u32 v0, v0, 2, 2
	v_bitop3_b32 v0, v1, v2, v0 bitop3:0x36
	v_add_u32_e32 v1, 0xa00, v150
	v_lshl_add_u32 v18, v0, 4, 0
	v_ashrrev_i32_e32 v0, 31, v1
	v_lshrrev_b32_e32 v0, 28, v0
	v_lshlrev_b32_e32 v114, 3, v2
	v_add_u32_e32 v2, v1, v0
	v_ashrrev_i32_e32 v0, 4, v2
	v_and_b32_e32 v2, -16, v2
	v_sub_u32_e32 v2, v1, v2
	v_ashrrev_i32_e32 v1, 31, v0
	v_lshlrev_b64 v[116:117], 8, v[0:1]
	v_lshlrev_b32_e32 v1, 2, v0
	v_lshlrev_b32_e32 v19, 8, v0
	v_and_b32_e32 v1, 12, v1
	v_bfe_u32 v0, v0, 2, 2
	v_bitop3_b32 v0, v1, v2, v0 bitop3:0x36
	v_add_u32_e32 v1, 0xc00, v150
	v_lshl_add_u32 v20, v0, 4, 0
	v_ashrrev_i32_e32 v0, 31, v1
	v_lshrrev_b32_e32 v0, 28, v0
	v_lshlrev_b32_e32 v118, 3, v2
	v_add_u32_e32 v2, v1, v0
	v_ashrrev_i32_e32 v0, 4, v2
	v_and_b32_e32 v2, -16, v2
	v_sub_u32_e32 v2, v1, v2
	v_ashrrev_i32_e32 v1, 31, v0
	v_lshlrev_b64 v[120:121], 8, v[0:1]
	v_lshlrev_b32_e32 v1, 2, v0
	v_lshlrev_b32_e32 v21, 8, v0
	v_and_b32_e32 v1, 12, v1
	v_bfe_u32 v0, v0, 2, 2
	v_lshlrev_b32_e32 v7, 2, v150
	v_bfe_u32 v8, v150, 4, 2
	v_and_b32_e32 v192, 15, v150
	v_bitop3_b32 v0, v1, v2, v0 bitop3:0x36
	v_add_u32_e32 v1, 0xe00, v150
	v_and_b32_e32 v7, 12, v7
	v_bfe_u32 v25, v150, 2, 2
	v_lshl_add_u32 v22, v0, 4, 0
	v_ashrrev_i32_e32 v0, 31, v1
	v_lshlrev_b32_e32 v6, 8, v192
	v_bitop3_b32 v26, v7, v8, v25 bitop3:0x36
	v_lshrrev_b32_e32 v0, 28, v0
	v_lshl_or_b32 v193, v26, 4, v6
	v_or_b32_e32 v26, 4, v8
	v_lshlrev_b32_e32 v122, 3, v2
	v_add_u32_e32 v2, v1, v0
	v_bitop3_b32 v26, v7, v26, v25 bitop3:0x36
	v_ashrrev_i32_e32 v0, 4, v2
	v_and_b32_e32 v2, -16, v2
	v_lshl_or_b32 v194, v26, 4, v6
	v_or_b32_e32 v26, 8, v8
	v_readlane_b32 s40, v247, 14
	v_sub_u32_e32 v2, v1, v2
	v_ashrrev_i32_e32 v1, 31, v0
	v_bitop3_b32 v26, v7, v26, v25 bitop3:0x36
	v_readlane_b32 s50, v247, 24
; #define LAS __attribute__((address_space(3)))
; __device__ __forceinline__ unsigned row_addr(int lane, int s) { return off_b((unsigned)(lane & 15), (unsigned)(4 * s + (lane >> 4))); }
; __device__ __forceinline__ void b_item(const Params& P, int layer, LAS unsigned char* lds, int item, int tid) {
;     const int b = item / 320, rem = item % 320, h = rem / 64, m = rem % 64, w = tid >> 6, lane = tid & 63;
;     const int qc = w >> 1, th = w & 1, g = lane >> 4, c15 = lane & 15;
;     const bf16_t* proj = (const bf16_t*)(P.ws + WS_PROJ);
;     const size_t tok0 = (size_t)b * SEQ + (size_t)m * 256;
;     LAS unsigned char* Qt = lds + 0; LAS unsigned char* KV = lds + 65536; LAS float* bias = (LAS float*)(lds + 131072);
;     tile_load<256, 16>(Qt, pjp(proj, BQ, 128, h, tok0), 128, tid);
;     for (int i = tid; i < 257; i += 512) bias[i] = P.rel_bias[(size_t)(layer * 5 + h) * 257 + i];
;     const int jst = (8 - 4 * m) > 0 ? (8 - 4 * m) : 0;
;     const long krow = (long)b * SEQ + (long)(4 * m - 8) * 64;
;     const bf16_t* kbase = pjp(proj, BKC, 128, h, 0) + krow * 128; const bf16_t* vbase = pjp(proj, BV, 128, h, 0) + krow * 128;
;     unsigned soff[2];
; #pragma unroll
;     for (int u = 0; u < 2; ++u) { const unsigned i = tid + 512 * u, row = i >> 4, ch = (i & 15) ^ (((row & 3u) << 2) | ((row >> 2) & 3u)); soff[u] = row * 128 + ch * 8; }
;     const unsigned ldsw = (unsigned)__builtin_amdgcn_readfirstlane(w) * 1024u;
;     ...
;     B_DMA(jst, 0);
;     __syncthreads();
;     LAS unsigned char* Qw = Qt + 4096 * (qc * 4 + th * 2);
;     float mrun[2] = {-1e30f, -1e30f}, lrun[2] = {0.f, 0.f}; const float bfar = bias[256];
;     unsigned kaddr[4], vaddr[8];
; #pragma unroll
;     for (int kk = 0; kk < 4; ++kk) kaddr[kk] = row_addr(lane, kk);
; #pragma unroll
;     for (int vb = 0; vb < 8; ++vb) vaddr[vb] = tr_addr<true>(lane, vb);
; __global__ __launch_bounds__(512, 2) void hybrid_fwd(Params P0) {
;     ...
;                 unsigned* ctr = (unsigned*)(P.ws + WS_END) + 3584 + layer; LAS int* sit = (LAS int*)(lds + 132608);
;                 for (;;) {
;                     if (tid == 0) *sit = (int)atomicAdd(ctr, 1u);
;                     __syncthreads();
;                     const int it = *sit;
;                     __syncthreads();
;                     if (it >= 640) break;
;                     b_item(P, layer, lds, it, tid);
	v_readlane_b32 s0, v247, 48
	v_lshlrev_b64 v[124:125], 8, v[0:1]
	v_lshlrev_b32_e32 v1, 2, v0
	v_lshl_or_b32 v195, v26, 4, v6
	v_or_b32_e32 v26, 12, v8
	v_readlane_b32 s51, v247, 25
	v_readlane_b32 s1, v247, 49
	s_add_u32 s8, s50, s0
	v_lshlrev_b32_e32 v23, 8, v0
	v_and_b32_e32 v1, 12, v1
	v_bfe_u32 v0, v0, 2, 2
	v_lshlrev_b32_e32 v4, 3, v150
	v_bitop3_b32 v7, v7, v26, v25 bitop3:0x36
	s_addc_u32 s9, s51, s1
	s_ashr_i32 s85, s84, 31
	v_lshlrev_b32_e32 v126, 3, v2
	v_bitop3_b32 v0, v1, v2, v0 bitop3:0x36
	v_and_b32_e32 v2, 0xffffff80, v4
	v_lshl_or_b32 v196, v7, 4, v6
	v_bfe_u32 v6, v150, 1, 1
	v_lshlrev_b32_e32 v7, 6, v150
	v_and_b32_e32 v25, 12, v150
	v_and_b32_e32 v4, 8, v4
	s_lshl_b64 s[0:1], s[84:85], 2
	v_or_b32_e32 v26, v8, v25
	v_and_or_b32 v197, v7, s92, v4
	v_bitop3_b32 v4, v8, v6, v25 bitop3:0x36
	s_add_u32 s0, s4, s0
	v_lshlrev_b32_e32 v198, 4, v4
	v_bitop3_b32 v4, v6, v26, 2 bitop3:0x36
	v_readlane_b32 s48, v247, 22
	s_addc_u32 s1, s5, s1
	v_lshlrev_b32_e32 v199, 4, v4
	v_bitop3_b32 v4, v6, v26, 4 bitop3:0x36
	v_readlane_b32 s49, v247, 23
	s_add_u32 s48, s0, 0x33983800
	v_lshlrev_b32_e32 v200, 4, v4
	v_bitop3_b32 v4, v6, v26, 6 bitop3:0x36
	s_addc_u32 s49, s1, 0
	v_lshlrev_b32_e32 v201, 4, v4
	v_bitop3_b32 v4, v6, v26, 8 bitop3:0x36
	v_ashrrev_i32_e32 v190, 6, v150
	s_add_u32 s60, s4, 0x18c00000
	v_lshlrev_b32_e32 v202, 4, v4
	v_bitop3_b32 v4, v6, v26, 10 bitop3:0x36
	v_ashrrev_i32_e32 v191, 7, v150
	v_and_b32_e32 v5, 1, v190
	s_addc_u32 s61, s5, 0
	v_lshlrev_b32_e32 v203, 4, v4
	v_bitop3_b32 v4, v6, v26, 12 bitop3:0x36
	s_add_u32 s39, s4, 0x1dc00000
	v_lshlrev_b32_e32 v204, 4, v4
	v_bitop3_b32 v4, v6, v26, 14 bitop3:0x36
	v_lshlrev_b32_e32 v25, 5, v5
	v_lshlrev_b32_e32 v6, 14, v191
	v_lshlrev_b32_e32 v5, 13, v5
	v_lshl_add_u32 v24, v0, 4, 0
	s_addc_u32 s62, s5, 0
	v_lshrrev_b32_e32 v0, 2, v150
	v_add3_u32 v206, 0, v6, v5
	v_max_i32_e32 v5, 0xffffff01, v150
	v_readlane_b32 s42, v247, 16
	v_readlane_b32 s43, v247, 17
	s_movk_i32 s0, 0x101
	v_bfe_u32 v1, v150, 6, 2
	v_and_b32_e32 v0, 12, v0
	s_add_u32 s63, s4, 0x1b400000
	v_sub_u32_e32 v5, v5, v150
	v_cmp_gt_i32_e64 s[42:43], s0, v150
	v_bitop3_b32 v0, v0, v192, v1 bitop3:0x36
	s_addc_u32 s64, s5, 0
	s_add_i32 s0, s94, 4
	v_add_u32_e32 v5, 0x1ff, v5
	v_lshl_or_b32 v0, v0, 3, v2
	v_lshrrev_b32_e32 v2, 2, v151
	s_cmp_lt_u32 s0, 11
	v_lshrrev_b32_e32 v6, 9, v5
	v_and_b32_e32 v2, 12, v2
	s_cselect_b32 s0, s93, 0x33984000
	v_add_u32_e32 v6, 1, v6
	v_readlane_b32 s44, v247, 18
	v_readlane_b32 s45, v247, 19
	v_readlane_b32 s46, v247, 20
	v_readlane_b32 s47, v247, 21
	v_bitop3_b32 v1, v2, v192, v1 bitop3:0x36
	v_lshlrev_b32_e32 v2, 3, v151
	s_add_u32 s18, s4, s0
	s_movk_i32 s0, 0x1ff
	v_and_b32_e32 v208, 0xfffffe, v6
	v_lshlrev_b32_e32 v136, 3, v8
	v_and_b32_e32 v2, 0xffffff80, v2
	v_lshlrev_b32_e32 v152, 6, v191
	v_cmp_lt_u32_e64 s[44:45], s0, v5
	v_cmp_ne_u32_e64 s[46:47], v6, v208
	v_lshl_add_u64 v[6:7], s[4:5], 0, v[136:137]
	s_mov_b64 s[0:1], 0x20400000
	v_readlane_b32 s41, v247, 15
	v_lshl_or_b32 v2, v1, 3, v2
	v_mov_b32_e32 v1, v137
	v_mov_b32_e32 v3, v137
	v_lshlrev_b32_e32 v205, 4, v4
	v_lshlrev_b32_e32 v4, 2, v8
	v_lshl_add_u64 v[156:157], v[6:7], 0, s[0:1]
	v_readlane_b32 s0, v247, 7
	v_or_b32_e32 v5, v152, v25
	v_cmp_eq_u32_e64 s[40:41], 0, v150
	v_ashrrev_i32_e32 v99, 31, v98
	v_ashrrev_i32_e32 v103, 31, v102
	v_ashrrev_i32_e32 v107, 31, v106
	v_ashrrev_i32_e32 v111, 31, v110
	v_ashrrev_i32_e32 v115, 31, v114
	v_ashrrev_i32_e32 v119, 31, v118
	v_ashrrev_i32_e32 v123, 31, v122
	v_ashrrev_i32_e32 v127, 31, v126
	v_add_u32_e32 v207, 8, v191
	v_ashrrev_i32_e32 v153, 31, v152
	s_addc_u32 s19, s5, 0
	v_or_b32_e32 v154, v25, v192
	v_lshl_add_u32 v209, v208, 9, v150
	v_add_u32_e32 v210, s0, v189
	v_sub_u32_e32 v211, v5, v4
	v_mad_i32_i24 v212, v8, -4, v5
	v_add_u32_e32 v213, v10, v9
	v_add_u32_e32 v214, v12, v11
	v_add_u32_e32 v215, v14, v13
	v_add_u32_e32 v216, v16, v15
	v_add_u32_e32 v217, v18, v17
	v_add_u32_e32 v218, v20, v19
	v_add_u32_e32 v219, v22, v21
	v_add_u32_e32 v220, v24, v23
	v_lshlrev_b32_e32 v136, 1, v4
	v_lshlrev_b64 v[158:159], 1, v[0:1]
	v_lshlrev_b64 v[160:161], 1, v[2:3]
	v_readlane_b32 s52, v247, 26
	v_readlane_b32 s53, v247, 27
	v_readlane_b32 s54, v247, 28
	v_readlane_b32 s55, v247, 29
	s_and_saveexec_b64 s[0:1], s[40:41]
	s_cbranch_execz .Lbq_pre_skip
	v_mov_b32_e32 v246, 1
	global_atomic_add v246, v137, v246, s[48:49] sc0
	s_waitcnt vmcnt(0)
